# attention tile loop: row constant cb applied to the row maximum instead of initialising all 16 score accumulators (13 VALU fewer per tile)
# speedup vs baseline: 1.0043x; 1.0029x over previous
; #define MFMA32(a, b, c) __builtin_amdgcn_mfma_f32_32x32x16_bf16((a), (b), (c), 0, 0, 0)
; DI void fox_attn_blk(const Params& P, unsigned char* lds, LAS unsigned char* ldsl, int tid, int G, float PRUNE, int pir) {
;     ...
;             DMA_TILE(QB0 - it - 4);
;             const int kt = qb - it;
;             if (it <= nvalid) {
;                 const unsigned char* tb = lds + ((kt + 120) % 12) * 10240;
;                 const float off = it == 0 ? 0.f : __int_as_float(__builtin_amdgcn_readlane(__float_as_int(offv), it - 1));
;                 bf16x8 kf[4]; f32x4 ck[4];
; #pragma unroll
;                 for (int ks = 0; ks < 4; ++ks) kf[ks] = *(const bf16x8*)(tb + koff + (((2 * ks + hi) ^ ksw) << 4));
; #pragma unroll
;                 for (int blk = 0; blk < 2; ++blk)
; #pragma unroll
;                     for (int s = 0; s < 2; ++s) vf[blk][s] = *(const bf16x8*)(tb + voff + blk * 2048 + (((2 * s + hi) ^ vsw) << 4));
; #pragma unroll
;                 for (int s = 0; s < 2; ++s) { ck[2 * s] = *(const f32x4*)(tb + 8192 + wvu * 256 + (16 * s + 8 * hi) * 4); ck[2 * s + 1] = *(const f32x4*)(tb + 8192 + wvu * 256 + (16 * s + 8 * hi) * 4 + 16); }
;                 const float cb = cq + off;
; #pragma unroll
;                 for (int i = 0; i < 16; ++i) sc[i] = cb;
; #pragma unroll
;                 for (int ks = 0; ks < 4; ++ks) sc = MFMA32(kf[ks], qf[ks], sc);
;                 float mx = -INFINITY;
; #pragma unroll
;                 for (int r = 0; r < 16; ++r) { const int kl = 16 * (r >> 3) + 8 * hi + (r & 7);
;                     float v = sc[r] - ck[r >> 2][r & 3];
;                     if (kt == qb && kl > r32) v = -INFINITY;
;                     sc[r] = v; mx = fmaxf(mx, v); }
;                 { const auto rr = __builtin_amdgcn_permlane32_swap(__float_as_uint(mx), __float_as_uint(mx), false, false);
;                   mx = fmaxf(__uint_as_float(rr[0]), __uint_as_float(rr[1])); }
;                 const float mnew = fmaxf(mrun, mx); alpha = __builtin_amdgcn_exp2f(mrun - mnew); mrun = mnew;
; #pragma unroll
;                 for (int r = 0; r < 16; ++r) sc[r] = __builtin_amdgcn_exp2f(sc[r] - mnew);
.LBB0_751:
	s_add_i32 s0, s33, 0xffffff8c
	s_max_i32 s0, s0, 4
	s_add_i32 s2, s0, -4
	s_mul_hi_i32 s0, s33, 0x2aaaaaab
	s_lshr_b32 s1, s0, 31
	s_lshr_b32 s0, s0, 1
	s_add_i32 s0, s0, s1
	s_mul_i32 s0, s0, 12
	s_sub_i32 s58, s33, s0
	v_mad_u64_u32 v[96:97], s[0:1], v168, s2, 0
	s_mulk_i32 s58, 0x2800
	s_add_i32 s0, s58, 0
	v_lshl_add_u64 v[96:97], v[96:97], 1, v[172:173]
	s_add_i32 m0, s0, s84
	s_lshl_b32 s62, s2, 5
	s_add_i32 s0, s0, s85
	global_load_lds_dwordx4 v[96:97], off
	v_lshl_add_u64 v[96:97], s[62:63], 2, v[166:167]
	s_add_i32 m0, s0, 0x2000
	s_add_i32 s58, s59, 1
	global_load_lds_dword v[96:97], off
	s_cmp_gt_u32 s58, s4
	s_mov_b64 s[0:1], 0
	s_cbranch_scc1 .LBB0_756
	v_add3_u32 v34, v1, s33, 4
	v_mul_hi_i32 v35, v34, s89
	v_lshrrev_b32_e32 v36, 31, v35
	v_lshrrev_b32_e32 v35, 1, v35
	v_add_u32_e32 v35, v35, v36
	v_mul_lo_u32 v35, v35, 12
	v_sub_u32_e32 v34, v34, v35
	v_mad_i32_i24 v92, v34, s90, 0
	v_add_u32_e32 v74, v92, v169
	v_add_u32_e32 v34, v74, v214
	s_add_i32 s0, s59, 64
	v_add_u32_e32 v35, v74, v215
	ds_read_b128 v[66:69], v34
	ds_read_b128 v[70:73], v35
	v_readlane_b32 s0, v91, s0
	s_and_b64 vcc, exec, s[56:57]
	s_nop 0
	v_add_f32_e32 v116, s0, v90
	s_mov_b64 s[0:1], -1
	s_waitcnt lgkmcnt(0)
	v_mfma_f32_32x32x16_bf16 v[34:49], v[66:69], v[50:53], 0
	v_add_u32_e32 v66, v74, v216
	ds_read_b128 v[66:69], v66
	v_mfma_f32_32x32x16_bf16 v[34:49], v[70:73], v[54:57], v[34:49]
	v_add_u32_e32 v70, v74, v217
	ds_read_b128 v[96:99], v70
	v_add_u32_e32 v70, v92, v196
	v_add_u32_e32 v71, v70, v218
	v_add_u32_e32 v95, v70, v219
	v_add3_u32 v92, v92, s85, v207
	ds_read_b128 v[74:77], v71 offset:4096
	ds_read_b128 v[70:73], v71 offset:6144
	s_waitcnt lgkmcnt(0)
	v_mfma_f32_32x32x16_bf16 v[34:49], v[66:69], v[58:61], v[34:49]
	ds_read_b128 v[78:81], v95 offset:4096
	ds_read_b128 v[66:69], v95 offset:6144
	ds_read_b128 v[100:103], v92 offset:8192
	ds_read_b128 v[104:107], v92 offset:8208
	ds_read_b128 v[108:111], v92 offset:8256
	ds_read_b128 v[112:115], v92 offset:8272
	v_mfma_f32_32x32x16_bf16 v[34:49], v[96:99], v[62:65], v[34:49]
	s_waitcnt lgkmcnt(0)
	s_nop 10
	v_sub_f32_e32 v34, v34, v100
	v_sub_f32_e32 v35, v35, v101
	v_sub_f32_e32 v36, v36, v102
	v_sub_f32_e32 v96, v37, v103
	v_max3_f32 v37, v34, s88, v35
	v_sub_f32_e32 v38, v38, v104
	v_sub_f32_e32 v39, v39, v105
	v_max3_f32 v37, v37, v36, v96
	v_sub_f32_e32 v97, v40, v106
	v_sub_f32_e32 v98, v41, v107
	v_max3_f32 v37, v37, v38, v39
	v_sub_f32_e32 v42, v42, v108
	v_sub_f32_e32 v43, v43, v109
	v_max3_f32 v37, v37, v97, v98
	v_sub_f32_e32 v99, v44, v110
	v_sub_f32_e32 v100, v45, v111
	v_max3_f32 v37, v37, v42, v43
	v_sub_f32_e32 v101, v46, v112
	v_sub_f32_e32 v102, v47, v113
	v_max3_f32 v37, v37, v99, v100
	v_sub_f32_e32 v103, v48, v114
	v_sub_f32_e32 v104, v49, v115
	v_max3_f32 v37, v37, v101, v102
	v_max3_f32 v37, v37, v103, v104
	v_mov_b32_e32 v40, v37
	s_nop 1
	v_permlane32_swap_b32_e32 v37, v40
	v_max_f32_e32 v37, v37, v40
	v_add_f32_e32 v37, v37, v116
	v_max_f32_e32 v95, v94, v37
	v_sub_f32_e32 v116, v95, v116
	v_sub_f32_e32 v34, v34, v116
	v_exp_f32_e32 v92, v34
	v_sub_f32_e32 v34, v35, v116
	v_exp_f32_e32 v37, v34
	v_sub_f32_e32 v34, v36, v116
	v_exp_f32_e32 v40, v34
	v_sub_f32_e32 v34, v96, v116
	v_exp_f32_e32 v44, v34
	v_sub_f32_e32 v34, v38, v116
	v_exp_f32_e32 v38, v34
	v_sub_f32_e32 v34, v39, v116
	v_exp_f32_e32 v41, v34
	v_sub_f32_e32 v34, v97, v116
	v_exp_f32_e32 v45, v34
	v_sub_f32_e32 v34, v98, v116
	v_exp_f32_e32 v46, v34
	v_sub_f32_e32 v34, v42, v116
	v_exp_f32_e32 v47, v34
	v_sub_f32_e32 v34, v43, v116
	v_exp_f32_e32 v48, v34
	v_sub_f32_e32 v34, v99, v116
	v_exp_f32_e32 v49, v34
	v_sub_f32_e32 v34, v100, v116
	v_exp_f32_e32 v35, v34
	v_sub_f32_e32 v34, v101, v116
	v_exp_f32_e32 v36, v34
	v_sub_f32_e32 v34, v102, v116
	v_exp_f32_e32 v39, v34
	v_sub_f32_e32 v34, v103, v116
	v_sub_f32_e32 v94, v94, v95
	v_exp_f32_e32 v42, v34
	v_sub_f32_e32 v34, v104, v116
	v_exp_f32_e32 v43, v34
	v_exp_f32_e32 v34, v94
	s_cbranch_vccnz .LBB0_757
	v_cmp_neq_f32_e32 vcc, 1.0, v34
	s_cbranch_vccz .LBB0_755
	v_pk_mul_f32 v[16:17], v[16:17], v[34:35] op_sel_hi:[1,0]
	v_pk_mul_f32 v[14:15], v[14:15], v[34:35] op_sel_hi:[1,0]
	v_pk_mul_f32 v[12:13], v[12:13], v[34:35] op_sel_hi:[1,0]
	v_pk_mul_f32 v[10:11], v[10:11], v[34:35] op_sel_hi:[1,0]
	v_pk_mul_f32 v[8:9], v[8:9], v[34:35] op_sel_hi:[1,0]
	v_pk_mul_f32 v[6:7], v[6:7], v[34:35] op_sel_hi:[1,0]
	v_pk_mul_f32 v[4:5], v[4:5], v[34:35] op_sel_hi:[1,0]
	v_pk_mul_f32 v[2:3], v[2:3], v[34:35] op_sel_hi:[1,0]
	v_pk_mul_f32 v[32:33], v[32:33], v[34:35] op_sel_hi:[1,0]
	v_pk_mul_f32 v[30:31], v[30:31], v[34:35] op_sel_hi:[1,0]
	v_pk_mul_f32 v[28:29], v[28:29], v[34:35] op_sel_hi:[1,0]
	v_pk_mul_f32 v[26:27], v[26:27], v[34:35] op_sel_hi:[1,0]
	v_pk_mul_f32 v[24:25], v[24:25], v[34:35] op_sel_hi:[1,0]
	v_pk_mul_f32 v[22:23], v[22:23], v[34:35] op_sel_hi:[1,0]
	v_pk_mul_f32 v[20:21], v[20:21], v[34:35] op_sel_hi:[1,0]
	v_pk_mul_f32 v[18:19], v[18:19], v[34:35] op_sel_hi:[1,0]
